# diff attention: waves 4-7 half a tile behind (3 LDS stages) with raised priority in the P.V section, on top of previous diff-loop changes
# speedup vs baseline: 1.0050x; 1.0050x over previous
.LBB0_139:
	s_barrier
	v_mov_b32_e32 v248, v108
	v_mov_b32_e32 v249, v92
	s_nop 1
	v_permlane16_swap_b32_e32 v108, v248
	v_permlane16_swap_b32_e32 v92, v249
	v_add_f32_e32 v108, v108, v248
	v_add_f32_e32 v92, v92, v249
	v_mov_b32_e32 v248, v108
	v_mov_b32_e32 v249, v92
	s_nop 1
	v_permlane32_swap_b32_e32 v108, v248
	v_permlane32_swap_b32_e32 v92, v249
	v_add_f32_e32 v108, v108, v248
	v_add_f32_e32 v92, v92, v249
	s_lshl_b64 s[0:1], s[6:7], 10
	s_add_u32 s0, s18, s0
	s_addc_u32 s1, s19, s1
	s_add_u32 s6, s0, s71
	s_addc_u32 s7, s1, 0
	v_div_scale_f32 v0, s[0:1], v108, v108, 1.0
	v_rcp_f32_e32 v1, v0
	v_lshlrev_b32_e32 v192, 1, v234
	s_add_i32 s70, s70, s76
	s_cmpk_lt_i32 s70, 0x100
	v_fma_f32 v2, -v0, v1, 1.0
	v_fmac_f32_e32 v1, v2, v1
	v_div_scale_f32 v2, vcc, 1.0, v108, 1.0
	v_mul_f32_e32 v3, v2, v1
	v_fma_f32 v4, -v0, v3, v2
	v_fmac_f32_e32 v3, v4, v1
	v_fma_f32 v0, -v0, v3, v2
	v_div_fmas_f32 v0, v0, v1, v3
	v_div_scale_f32 v1, s[0:1], v92, v92, v225
	v_rcp_f32_e32 v2, v1
	v_div_fixup_f32 v0, v0, v108, 1.0
	s_mov_b64 s[0:1], 0x800000
	v_fma_f32 v3, -v1, v2, 1.0
	v_fmac_f32_e32 v2, v3, v2
	v_div_scale_f32 v3, vcc, v225, v92, v225
	v_mul_f32_e32 v4, v3, v2
	v_fma_f32 v5, -v1, v4, v3
	v_fmac_f32_e32 v4, v5, v2
	v_fma_f32 v1, -v1, v4, v3
	v_div_fmas_f32 v1, v1, v2, v4
	v_div_fixup_f32 v2, v1, v92, v225
	v_pk_mul_f32 v[4:5], v[124:125], v[2:3] op_sel_hi:[1,0]
	v_pk_mul_f32 v[6:7], v[126:127], v[2:3] op_sel_hi:[1,0]
	v_pk_fma_f32 v[4:5], v[120:121], v[0:1], v[4:5] op_sel_hi:[1,0,1] neg_lo:[0,0,1] neg_hi:[0,0,1]
	v_pk_fma_f32 v[6:7], v[122:123], v[0:1], v[6:7] op_sel_hi:[1,0,1] neg_lo:[0,0,1] neg_hi:[0,0,1]
	v_mul_f32_e32 v1, v5, v5
	v_mul_f32_e32 v3, v7, v7
	v_fmac_f32_e32 v1, v4, v4
	v_fmac_f32_e32 v3, v6, v6
	v_add_f32_e32 v1, v1, v3
	v_pk_mul_f32 v[8:9], v[116:117], v[2:3] op_sel_hi:[1,0]
	v_pk_mul_f32 v[10:11], v[118:119], v[2:3] op_sel_hi:[1,0]
	v_pk_fma_f32 v[8:9], v[112:113], v[0:1], v[8:9] op_sel_hi:[1,0,1] neg_lo:[0,0,1] neg_hi:[0,0,1]
	v_pk_fma_f32 v[10:11], v[114:115], v[0:1], v[10:11] op_sel_hi:[1,0,1] neg_lo:[0,0,1] neg_hi:[0,0,1]
	v_mul_f32_e32 v3, v9, v9
	v_mul_f32_e32 v12, v11, v11
	v_fmac_f32_e32 v3, v8, v8
	v_fmac_f32_e32 v12, v10, v10
	v_add_f32_e32 v3, v3, v12
	v_add_f32_e32 v1, v1, v3
	v_pk_mul_f32 v[12:13], v[104:105], v[2:3] op_sel_hi:[1,0]
	v_pk_mul_f32 v[14:15], v[106:107], v[2:3] op_sel_hi:[1,0]
	v_pk_fma_f32 v[12:13], v[96:97], v[0:1], v[12:13] op_sel_hi:[1,0,1] neg_lo:[0,0,1] neg_hi:[0,0,1]
	v_pk_fma_f32 v[14:15], v[98:99], v[0:1], v[14:15] op_sel_hi:[1,0,1] neg_lo:[0,0,1] neg_hi:[0,0,1]
	v_mul_f32_e32 v3, v13, v13
	s_waitcnt vmcnt(3)
	v_mul_f32_e32 v16, v15, v15
	v_fmac_f32_e32 v3, v12, v12
	v_fmac_f32_e32 v16, v14, v14
	v_add_f32_e32 v3, v3, v16
	v_add_f32_e32 v1, v3, v1
	v_pk_mul_f32 v[16:17], v[88:89], v[2:3] op_sel_hi:[1,0]
	v_pk_mul_f32 v[18:19], v[90:91], v[2:3] op_sel_hi:[1,0]
	v_pk_fma_f32 v[16:17], v[84:85], v[0:1], v[16:17] op_sel_hi:[1,0,1] neg_lo:[0,0,1] neg_hi:[0,0,1]
	v_pk_fma_f32 v[18:19], v[86:87], v[0:1], v[18:19] op_sel_hi:[1,0,1] neg_lo:[0,0,1] neg_hi:[0,0,1]
	v_mul_f32_e32 v3, v17, v17
	s_waitcnt vmcnt(2)
	v_mul_f32_e32 v20, v19, v19
	v_fmac_f32_e32 v3, v16, v16
	v_fmac_f32_e32 v20, v18, v18
	v_add_f32_e32 v3, v3, v20
	v_add_f32_e32 v1, v3, v1
	v_pk_mul_f32 v[20:21], v[76:77], v[2:3] op_sel_hi:[1,0]
	v_pk_mul_f32 v[22:23], v[78:79], v[2:3] op_sel_hi:[1,0]
	v_pk_fma_f32 v[20:21], v[68:69], v[0:1], v[20:21] op_sel_hi:[1,0,1] neg_lo:[0,0,1] neg_hi:[0,0,1]
	v_pk_fma_f32 v[22:23], v[70:71], v[0:1], v[22:23] op_sel_hi:[1,0,1] neg_lo:[0,0,1] neg_hi:[0,0,1]
	v_mul_f32_e32 v3, v21, v21
	s_waitcnt vmcnt(1)
	v_mul_f32_e32 v24, v23, v23
	v_fmac_f32_e32 v3, v20, v20
	v_fmac_f32_e32 v24, v22, v22
	v_add_f32_e32 v3, v3, v24
	v_add_f32_e32 v1, v3, v1
	v_pk_mul_f32 v[24:25], v[64:65], v[2:3] op_sel_hi:[1,0]
	v_pk_mul_f32 v[26:27], v[66:67], v[2:3] op_sel_hi:[1,0]
	v_pk_fma_f32 v[24:25], v[60:61], v[0:1], v[24:25] op_sel_hi:[1,0,1] neg_lo:[0,0,1] neg_hi:[0,0,1]
	v_pk_fma_f32 v[26:27], v[62:63], v[0:1], v[26:27] op_sel_hi:[1,0,1] neg_lo:[0,0,1] neg_hi:[0,0,1]
	v_mul_f32_e32 v3, v25, v25
	s_waitcnt vmcnt(0)
	v_mul_f32_e32 v28, v27, v27
	v_fmac_f32_e32 v3, v24, v24
	v_fmac_f32_e32 v28, v26, v26
	v_add_f32_e32 v3, v3, v28
	v_add_f32_e32 v1, v3, v1
	v_pk_mul_f32 v[28:29], v[52:53], v[2:3] op_sel_hi:[1,0]
	v_pk_mul_f32 v[30:31], v[54:55], v[2:3] op_sel_hi:[1,0]
	v_pk_fma_f32 v[28:29], v[48:49], v[0:1], v[28:29] op_sel_hi:[1,0,1] neg_lo:[0,0,1] neg_hi:[0,0,1]
	v_pk_fma_f32 v[30:31], v[50:51], v[0:1], v[30:31] op_sel_hi:[1,0,1] neg_lo:[0,0,1] neg_hi:[0,0,1]
	v_mul_f32_e32 v3, v29, v29
	v_mul_f32_e32 v40, v31, v31
	v_fmac_f32_e32 v3, v28, v28
	v_fmac_f32_e32 v40, v30, v30
	v_add_f32_e32 v3, v3, v40
	v_add_f32_e32 v40, v3, v1
	v_pk_mul_f32 v[36:37], v[36:37], v[2:3] op_sel_hi:[1,0]
	v_pk_mul_f32 v[2:3], v[38:39], v[2:3] op_sel_hi:[1,0]
	s_nop 0
	v_pk_fma_f32 v[2:3], v[34:35], v[0:1], v[2:3] op_sel_hi:[1,0,1] neg_lo:[0,0,1] neg_hi:[0,0,1]
	v_pk_fma_f32 v[0:1], v[32:33], v[0:1], v[36:37] op_sel_hi:[1,0,1] neg_lo:[0,0,1] neg_hi:[0,0,1]
	v_mul_f32_e32 v33, v3, v3
	v_mul_f32_e32 v32, v1, v1
	v_fmac_f32_e32 v32, v0, v0
	v_fmac_f32_e32 v33, v2, v2
	v_add_f32_e32 v32, v32, v33
	v_add_f32_e32 v32, v32, v40
	v_mov_b32_e32 v33, v32
	s_nop 1
	v_permlane16_swap_b32_e32 v32, v33
	v_add_f32_e32 v32, v32, v33
	v_mov_b32_e32 v33, v32
	s_nop 1
	v_permlane32_swap_b32_e32 v32, v33
	v_add_f32_e32 v32, v32, v33
	v_fmamk_f32 v32, v32, 0x3c000000, v221
	v_cmp_gt_f32_e32 vcc, s97, v32
	v_mul_f32_e32 v33, 0x4b800000, v32
	v_lshlrev_b64 v[34:35], 10, v[202:203]
	v_cndmask_b32_e32 v32, v32, v33, vcc
	v_rsq_f32_e32 v32, v32
	v_lshl_add_u64 v[34:35], s[6:7], 0, v[34:35]
	v_lshl_add_u64 v[34:35], v[34:35], 0, v[192:193]
	v_lshl_add_u64 v[36:37], v[34:35], 0, s[0:1]
	v_mul_f32_e32 v33, 0x45800000, v32
	v_cndmask_b32_e32 v32, v32, v33, vcc
	v_mul_f32_e32 v32, v226, v32
	v_pk_mul_f32 v[6:7], v[6:7], v[32:33] op_sel_hi:[1,0]
	v_pk_mul_f32 v[4:5], v[4:5], v[32:33] op_sel_hi:[1,0]
	v_pk_mul_f32 v[2:3], v[2:3], v[32:33] op_sel_hi:[1,0]
	v_cvt_pk_bf16_f32 v4, v4, v5
	v_cvt_pk_bf16_f32 v5, v6, v7
	v_add_co_u32_e32 v6, vcc, s97, v34
	v_pk_mul_f32 v[0:1], v[0:1], v[32:33] op_sel_hi:[1,0]
	s_nop 0
	v_addc_co_u32_e32 v7, vcc, 0, v35, vcc
	global_store_dwordx2 v[6:7], v[4:5], off
	v_pk_mul_f32 v[4:5], v[10:11], v[32:33] op_sel_hi:[1,0]
	v_pk_mul_f32 v[6:7], v[8:9], v[32:33] op_sel_hi:[1,0]
	v_cvt_pk_bf16_f32 v0, v0, v1
	v_cvt_pk_bf16_f32 v6, v6, v7
	v_cvt_pk_bf16_f32 v7, v4, v5
	global_store_dwordx2 v[36:37], v[6:7], off offset:32
	v_pk_mul_f32 v[4:5], v[14:15], v[32:33] op_sel_hi:[1,0]
	v_pk_mul_f32 v[6:7], v[12:13], v[32:33] op_sel_hi:[1,0]
	v_cvt_pk_bf16_f32 v1, v2, v3
	v_cvt_pk_bf16_f32 v6, v6, v7
	v_cvt_pk_bf16_f32 v7, v4, v5
	global_store_dwordx2 v[36:37], v[6:7], off offset:64
	v_pk_mul_f32 v[4:5], v[18:19], v[32:33] op_sel_hi:[1,0]
	v_pk_mul_f32 v[6:7], v[16:17], v[32:33] op_sel_hi:[1,0]
	global_store_dwordx2 v[36:37], v[0:1], off offset:224
	v_cvt_pk_bf16_f32 v6, v6, v7
	v_cvt_pk_bf16_f32 v7, v4, v5
	global_store_dwordx2 v[36:37], v[6:7], off offset:96
	v_pk_mul_f32 v[4:5], v[22:23], v[32:33] op_sel_hi:[1,0]
	v_pk_mul_f32 v[6:7], v[20:21], v[32:33] op_sel_hi:[1,0]
	s_nop 0
	v_cvt_pk_bf16_f32 v6, v6, v7
	v_cvt_pk_bf16_f32 v7, v4, v5
	global_store_dwordx2 v[36:37], v[6:7], off offset:128
	v_pk_mul_f32 v[4:5], v[26:27], v[32:33] op_sel_hi:[1,0]
	v_pk_mul_f32 v[6:7], v[24:25], v[32:33] op_sel_hi:[1,0]
	s_nop 0
	v_cvt_pk_bf16_f32 v6, v6, v7
	v_cvt_pk_bf16_f32 v7, v4, v5
	global_store_dwordx2 v[36:37], v[6:7], off offset:160
	v_pk_mul_f32 v[4:5], v[30:31], v[32:33] op_sel_hi:[1,0]
	v_pk_mul_f32 v[6:7], v[28:29], v[32:33] op_sel_hi:[1,0]
	s_nop 0
	v_cvt_pk_bf16_f32 v6, v6, v7
	v_cvt_pk_bf16_f32 v7, v4, v5
	global_store_dwordx2 v[36:37], v[6:7], off offset:192
	s_cbranch_scc0 .LBB0_155

.LBB0_146:
	v_exp_f32_e32 v52, v52
	v_exp_f32_e32 v53, v53
	v_exp_f32_e32 v54, v54
	v_exp_f32_e32 v55, v55
	v_exp_f32_e32 v48, v48
	v_exp_f32_e32 v49, v49
	v_exp_f32_e32 v56, v56
	v_exp_f32_e32 v57, v57
	v_exp_f32_e32 v58, v58
	v_exp_f32_e32 v59, v59
	v_add_f32_e32 v249, v52, v53
	v_add_f32_e32 v249, v249, v54
	v_add_f32_e32 v249, v249, v55
	v_add_f32_e32 v249, v249, v56
	v_add_f32_e32 v249, v249, v57
	v_add_f32_e32 v249, v249, v58
	v_add_f32_e32 v249, v249, v59
	v_exp_f32_e32 v68, v68
	v_exp_f32_e32 v69, v69
	v_exp_f32_e32 v70, v70
	v_exp_f32_e32 v71, v71
	v_exp_f32_e32 v80, v72
	v_exp_f32_e32 v81, v73
	v_exp_f32_e32 v82, v74
	v_exp_f32_e32 v83, v75
	v_cvt_pk_bf16_f32 v72, v52, v53
	v_cvt_pk_bf16_f32 v73, v54, v55
	v_add_f32_e32 v249, v249, v68
	v_add_f32_e32 v249, v249, v69
	v_add_f32_e32 v249, v249, v70
	v_add_f32_e32 v249, v249, v71
	v_add_f32_e32 v249, v249, v80
	v_add_f32_e32 v249, v249, v81
	v_add_f32_e32 v249, v249, v82
	v_add_f32_e32 v249, v249, v83
	v_exp_f32_e32 v50, v50
	v_exp_f32_e32 v51, v51
	v_exp_f32_e32 v52, v60
	v_exp_f32_e32 v53, v61
	v_exp_f32_e32 v54, v62
	v_exp_f32_e32 v55, v63
	v_exp_f32_e32 v60, v64
	v_exp_f32_e32 v61, v65
	v_exp_f32_e32 v62, v66
	v_exp_f32_e32 v63, v67
	v_exp_f32_e32 v64, v76
	v_exp_f32_e32 v65, v77
	v_exp_f32_e32 v66, v78
	v_exp_f32_e32 v67, v79
	v_lshlrev_b32_e32 v234, 2, v93
	v_add_f32_e32 v248, v48, v49
	v_add_f32_e32 v248, v248, v50
	v_add_f32_e32 v248, v248, v51
	v_add_f32_e32 v248, v248, v52
	v_add_f32_e32 v248, v248, v53
	v_add_f32_e32 v248, v248, v54
	v_add_f32_e32 v248, v248, v55
	v_add_f32_e32 v248, v248, v60
	v_add_f32_e32 v248, v248, v61
	v_add_f32_e32 v248, v248, v62
	v_add_f32_e32 v248, v248, v63
	v_add_f32_e32 v248, v248, v64
	v_add_f32_e32 v248, v248, v65
	v_add_f32_e32 v248, v248, v66
	v_add_f32_e32 v248, v248, v67
	v_and_or_b32 v95, v234, 4, v94
	v_cvt_pk_bf16_f32 v100, v48, v49
	s_waitcnt lgkmcnt(0)
	s_barrier
	v_lshlrev_b32_e32 v48, 3, v92
	v_cvt_pk_bf16_f32 v74, v56, v57
	v_cvt_pk_bf16_f32 v75, v58, v59
	v_cvt_pk_bf16_f32 v56, v68, v69
	v_cvt_pk_bf16_f32 v57, v70, v71
	v_cvt_pk_bf16_f32 v58, v80, v81
	v_cvt_pk_bf16_f32 v59, v82, v83
	v_cvt_pk_bf16_f32 v101, v50, v51
	v_cvt_pk_bf16_f32 v102, v52, v53
	v_cvt_pk_bf16_f32 v103, v54, v55
	v_cvt_pk_bf16_f32 v80, v60, v61
	v_cvt_pk_bf16_f32 v81, v62, v63
	v_cvt_pk_bf16_f32 v82, v64, v65
	v_cvt_pk_bf16_f32 v83, v66, v67
	v_lshlrev_b32_e32 v235, 11, v93
	v_lshlrev_b32_e32 v236, 8, v94
	v_and_b32_e32 v237, 24, v48
	v_lshlrev_b32_e32 v238, 5, v95
	v_lshl_add_u64 v[212:213], v[84:85], 1, s[8:9]
	v_lshl_add_u64 v[214:215], v[86:87], 1, s[8:9]
	v_lshl_add_u64 v[216:217], v[88:89], 1, s[8:9]
	v_lshl_add_u64 v[218:219], v[90:91], 1, s[8:9]
	v_mov_b64_e32 v[54:55], v[38:39]
	v_mov_b64_e32 v[50:51], v[34:35]
	v_mov_b64_e32 v[66:67], v[38:39]
	v_mov_b64_e32 v[62:63], v[34:35]
	v_mov_b64_e32 v[78:79], v[38:39]
	v_mov_b64_e32 v[70:71], v[34:35]
	v_mov_b64_e32 v[90:91], v[38:39]
	v_mov_b64_e32 v[86:87], v[34:35]
	v_mov_b64_e32 v[106:107], v[38:39]
	v_mov_b64_e32 v[98:99], v[34:35]
	v_mov_b64_e32 v[118:119], v[38:39]
	v_mov_b64_e32 v[114:115], v[34:35]
	v_mov_b64_e32 v[126:127], v[38:39]
	v_mov_b64_e32 v[122:123], v[34:35]
	v_mov_b64_e32 v[94:95], v[38:39]
	v_mov_b64_e32 v[110:111], v[34:35]
	v_ashrrev_i32_e32 v203, 31, v202
	s_mov_b32 s1, 0
	v_mov_b64_e32 v[52:53], v[36:37]
	v_mov_b64_e32 v[48:49], v[32:33]
	v_mov_b64_e32 v[64:65], v[36:37]
	v_mov_b64_e32 v[60:61], v[32:33]
	v_mov_b64_e32 v[76:77], v[36:37]
	v_mov_b64_e32 v[68:69], v[32:33]
	v_mov_b64_e32 v[88:89], v[36:37]
	v_mov_b64_e32 v[84:85], v[32:33]
	v_mov_b64_e32 v[104:105], v[36:37]
	v_mov_b64_e32 v[96:97], v[32:33]
	v_mov_b64_e32 v[116:117], v[36:37]
	v_mov_b64_e32 v[112:113], v[32:33]
	v_mov_b64_e32 v[124:125], v[36:37]
	v_mov_b64_e32 v[120:121], v[32:33]
	v_mov_b32_e32 v92, v36
	v_mov_b32_e32 v93, v248
	v_mov_b32_e32 v108, v32
	v_mov_b32_e32 v109, v249
	v_readfirstlane_b32 s100, v220
	s_mov_b32 s98, 0
	s_mov_b32 s99, 0x9000
	s_lshr_b32 s100, s100, 8
.LBB0_147:
	s_mov_b32 s0, s98
	s_mov_b32 s8, s99
	v_add3_u32 v247, s0, v192, v233
	ds_read_b128 v[156:159], v247
	ds_read_b128 v[152:155], v247 offset:128
	ds_read_b128 v[148:151], v247 offset:64
	ds_read_b128 v[144:147], v247 offset:192
	ds_read_b128 v[140:143], v247 offset:1280
	ds_read_b128 v[136:139], v247 offset:1408
	ds_read_b128 v[132:135], v247 offset:1344
	ds_read_b128 v[128:131], v247 offset:1472
	v_add_u32_e32 v160, s0, v235
	v_add3_u32 v160, v160, v236, v237
	v_xor_b32_e32 v161, 32, v238
	v_add_u32_e32 v245, v160, v161
	v_xor_b32_e32 v161, 64, v238
	v_add_u32_e32 v244, v160, v161
	v_xor_b32_e32 v161, 0x60, v238
	v_add_u32_e32 v243, v160, v161
	v_xor_b32_e32 v161, 0x80, v238
	v_add_u32_e32 v242, v160, v161
	v_xor_b32_e32 v161, 0xa0, v238
	v_add_u32_e32 v241, v160, v161
	v_xor_b32_e32 v161, 0xc0, v238
	v_add_u32_e32 v240, v160, v161
	v_xor_b32_e32 v161, 0xe0, v238
	v_add_u32_e32 v246, v160, v238
	v_add_u32_e32 v239, v160, v161
	v_add3_u32 v160, s8, v205, v207
	v_add3_u32 v161, s8, v227, v228
	s_waitcnt vmcnt(3)
	ds_write_b128 v160, v[16:19]
	v_add_u32_e32 v160, s8, v209
	s_waitcnt vmcnt(2)
	ds_write_b128 v161, v[20:23]
	v_add3_u32 v160, v160, v211, v229
	v_add_u32_e32 v161, s8, v230
	s_waitcnt vmcnt(1)
	ds_write_b128 v160, v[24:27] offset:20480
	v_add3_u32 v161, v161, v231, v232
	s_add_i32 s8, s1, 3
	s_add_i32 s0, s1, 2
	s_waitcnt vmcnt(0)
	ds_write_b128 v161, v[28:31] offset:20480
	s_min_u32 s8, s8, s83
	s_min_u32 s0, s0, s83
	s_lshl_b32 s8, s8, 6
	s_lshl_b32 s0, s0, 6
	v_add_u32_e32 v16, s8, v204
	v_add_u32_e32 v164, s8, v206
	v_add_u32_e32 v184, s0, v208
	v_add_u32_e32 v28, s0, v210
	v_ashrrev_i32_e32 v17, 31, v16
	v_ashrrev_i32_e32 v165, 31, v164
	v_ashrrev_i32_e32 v185, 31, v184
	v_ashrrev_i32_e32 v29, 31, v28
	v_lshlrev_b64 v[16:17], 11, v[16:17]
	v_lshlrev_b64 v[20:21], 11, v[164:165]
	v_lshlrev_b64 v[24:25], 11, v[184:185]
	v_lshlrev_b64 v[28:29], 11, v[28:29]
	v_lshl_add_u64 v[16:17], v[212:213], 0, v[16:17]
	v_lshl_add_u64 v[20:21], v[214:215], 0, v[20:21]
	v_lshl_add_u64 v[24:25], v[216:217], 0, v[24:25]
	v_lshl_add_u64 v[28:29], v[218:219], 0, v[28:29]
	global_load_dwordx4 v[16:19], v[16:17], off
	global_load_dwordx4 v[20:23], v[20:21], off
	global_load_dwordx4 v[24:27], v[24:25], off offset:1024
	global_load_dwordx4 v[28:31], v[28:29], off offset:1024
	s_waitcnt lgkmcnt(11)
	v_mfma_f32_16x16x32_bf16 v[188:191], v[156:159], v[0:3], v[40:43]
	ds_read_b128 v[156:159], v247 offset:10240
	s_waitcnt lgkmcnt(11)
	v_mfma_f32_16x16x32_bf16 v[160:163], v[152:155], v[8:11], v[44:47]
	ds_read_b128 v[152:155], v247 offset:10368
	s_waitcnt lgkmcnt(11)
	v_mfma_f32_16x16x32_bf16 v[188:191], v[148:151], v[4:7], v[188:191]
	ds_read_b128 v[148:151], v247 offset:10304
	s_waitcnt lgkmcnt(11)
	v_mfma_f32_16x16x32_bf16 v[160:163], v[144:147], v[12:15], v[160:163]
	ds_read_b128 v[144:147], v247 offset:10432
	s_waitcnt lgkmcnt(11)
	v_mfma_f32_16x16x32_bf16 v[184:187], v[140:143], v[0:3], v[40:43]
	ds_read_b128 v[140:143], v247 offset:11520
	s_waitcnt lgkmcnt(11)
	v_mfma_f32_16x16x32_bf16 v[168:171], v[136:139], v[8:11], v[44:47]
	ds_read_b128 v[136:139], v247 offset:11648
	s_waitcnt lgkmcnt(11)
	v_mfma_f32_16x16x32_bf16 v[184:187], v[132:135], v[4:7], v[184:187]
	ds_read_b128 v[132:135], v247 offset:11584
	s_waitcnt lgkmcnt(11)
	v_mfma_f32_16x16x32_bf16 v[168:171], v[128:131], v[12:15], v[168:171]
	ds_read_b128 v[128:131], v247 offset:11712
	s_waitcnt lgkmcnt(7)
	v_mfma_f32_16x16x32_bf16 v[180:183], v[156:159], v[0:3], v[40:43]
	ds_read_b64_tr_b16 v[156:157], v246 offset:20480
	ds_read_b64_tr_b16 v[158:159], v246 offset:21504
	s_waitcnt lgkmcnt(8)
	v_mfma_f32_16x16x32_bf16 v[164:167], v[152:155], v[8:11], v[44:47]
	ds_read_b64_tr_b16 v[152:153], v245 offset:20480
	ds_read_b64_tr_b16 v[154:155], v245 offset:21504
	s_waitcnt lgkmcnt(9)
	v_mfma_f32_16x16x32_bf16 v[180:183], v[148:151], v[4:7], v[180:183]
	ds_read_b64_tr_b16 v[148:149], v244 offset:20480
	ds_read_b64_tr_b16 v[150:151], v244 offset:21504
	s_waitcnt lgkmcnt(10)
	v_mfma_f32_16x16x32_bf16 v[164:167], v[144:147], v[12:15], v[164:167]
	ds_read_b64_tr_b16 v[144:145], v243 offset:20480
	ds_read_b64_tr_b16 v[146:147], v243 offset:21504
	s_waitcnt lgkmcnt(11)
	v_mfma_f32_16x16x32_bf16 v[172:175], v[140:143], v[0:3], v[40:43]
	ds_read_b64_tr_b16 v[140:141], v242 offset:20480
	ds_read_b64_tr_b16 v[142:143], v242 offset:21504
	s_waitcnt lgkmcnt(12)
	v_mfma_f32_16x16x32_bf16 v[176:179], v[136:139], v[8:11], v[44:47]
	ds_read_b64_tr_b16 v[136:137], v241 offset:20480
	ds_read_b64_tr_b16 v[138:139], v241 offset:21504
	s_waitcnt lgkmcnt(13)
	v_mfma_f32_16x16x32_bf16 v[172:175], v[132:135], v[4:7], v[172:175]
	ds_read_b64_tr_b16 v[132:133], v240 offset:20480
	ds_read_b64_tr_b16 v[134:135], v240 offset:21504
	s_waitcnt lgkmcnt(14)
	v_mfma_f32_16x16x32_bf16 v[176:179], v[128:131], v[12:15], v[176:179]
	ds_read_b64_tr_b16 v[128:129], v239 offset:20480
	ds_read_b64_tr_b16 v[130:131], v239 offset:21504
	s_add_i32 s8, s1, 1
	s_cmp_ge_u32 s8, s82
	s_cbranch_scc1 .LBB0_153
	s_cmp_lg_u32 s1, 0
	s_cselect_b64 s[0:1], -1, 0
	s_and_b32 s9, s8, 3
	s_cmp_lg_u32 s9, 0
	s_cselect_b64 s[14:15], -1, 0
	s_and_b64 s[0:1], s[0:1], s[14:15]
	s_and_b64 vcc, exec, s[0:1]
	s_cbranch_vccnz .LBB0_153
	v_max_f32_e32 v194, v189, v189
	v_max_f32_e32 v195, v188, v188
	v_max_f32_e32 v194, v195, v194
	v_max3_f32 v194, v194, v190, v191
	v_max3_f32 v194, v194, v184, v185
	v_max3_f32 v194, v194, v186, v187
	v_max3_f32 v194, v194, v180, v181
	v_max3_f32 v194, v194, v182, v183
	v_max3_f32 v194, v194, v172, v173
	v_max3_f32 v194, v194, v174, v175
	v_mov_b32_e32 v195, v194
	s_nop 1
	v_permlane16_swap_b32_e32 v194, v195
	v_max_f32_e32 v195, v195, v195
	v_max_f32_e32 v194, v194, v194
	v_max_f32_e32 v194, v194, v195
	v_mov_b32_e32 v195, v194
	s_nop 1
	v_permlane32_swap_b32_e32 v194, v195
	v_max_f32_e32 v195, v195, v195
	v_max_f32_e32 v194, v194, v194
	v_max_f32_e32 v247, v194, v195
	v_cmp_lt_f32_e32 vcc, s44, v247
	s_cbranch_vccz .LBB0_151
	s_nop 0
	v_cndmask_b32_e32 v247, 0, v247, vcc
	v_exp_f32_e64 v194, -v247
	v_lshlrev_b32_e32 v196, 16, v72
	v_and_b32_e32 v197, 0xffff0000, v72
	v_sub_f32_e32 v191, v191, v247
	v_pk_mul_f32 v[196:197], v[194:195], v[196:197] op_sel_hi:[0,1]
	v_cvt_pk_bf16_f32 v72, v196, v197
	v_lshlrev_b32_e32 v196, 16, v73
	v_and_b32_e32 v197, 0xffff0000, v73
	v_pk_mul_f32 v[196:197], v[194:195], v[196:197] op_sel_hi:[0,1]
	v_cvt_pk_bf16_f32 v73, v196, v197
	v_lshlrev_b32_e32 v196, 16, v74
	v_and_b32_e32 v197, 0xffff0000, v74
	v_pk_mul_f32 v[196:197], v[194:195], v[196:197] op_sel_hi:[0,1]
	v_cvt_pk_bf16_f32 v74, v196, v197
	v_lshlrev_b32_e32 v196, 16, v75
	v_and_b32_e32 v197, 0xffff0000, v75
	v_pk_mul_f32 v[196:197], v[194:195], v[196:197] op_sel_hi:[0,1]
	v_cvt_pk_bf16_f32 v75, v196, v197
	v_lshlrev_b32_e32 v196, 16, v56
	v_and_b32_e32 v197, 0xffff0000, v56
	v_pk_mul_f32 v[196:197], v[194:195], v[196:197] op_sel_hi:[0,1]
	v_cvt_pk_bf16_f32 v56, v196, v197
	v_lshlrev_b32_e32 v196, 16, v57
	v_and_b32_e32 v197, 0xffff0000, v57
	v_pk_mul_f32 v[196:197], v[194:195], v[196:197] op_sel_hi:[0,1]
	v_cvt_pk_bf16_f32 v57, v196, v197
	v_lshlrev_b32_e32 v196, 16, v58
	v_and_b32_e32 v197, 0xffff0000, v58
	v_pk_mul_f32 v[196:197], v[194:195], v[196:197] op_sel_hi:[0,1]
	v_cvt_pk_bf16_f32 v58, v196, v197
	v_lshlrev_b32_e32 v196, 16, v59
	v_and_b32_e32 v197, 0xffff0000, v59
	v_pk_mul_f32 v[110:111], v[110:111], v[194:195] op_sel_hi:[1,0]
	v_pk_mul_f32 v[108:109], v[108:109], v[194:195] op_sel_hi:[1,0]
	v_pk_mul_f32 v[122:123], v[122:123], v[194:195] op_sel_hi:[1,0]
	v_pk_mul_f32 v[120:121], v[120:121], v[194:195] op_sel_hi:[1,0]
	v_pk_mul_f32 v[114:115], v[114:115], v[194:195] op_sel_hi:[1,0]
	v_pk_mul_f32 v[112:113], v[112:113], v[194:195] op_sel_hi:[1,0]
	v_pk_mul_f32 v[98:99], v[98:99], v[194:195] op_sel_hi:[1,0]
	v_pk_mul_f32 v[96:97], v[96:97], v[194:195] op_sel_hi:[1,0]
	v_pk_mul_f32 v[86:87], v[86:87], v[194:195] op_sel_hi:[1,0]
	v_pk_mul_f32 v[84:85], v[84:85], v[194:195] op_sel_hi:[1,0]
	v_pk_mul_f32 v[70:71], v[70:71], v[194:195] op_sel_hi:[1,0]
	v_pk_mul_f32 v[68:69], v[68:69], v[194:195] op_sel_hi:[1,0]
	v_pk_mul_f32 v[62:63], v[62:63], v[194:195] op_sel_hi:[1,0]
	v_pk_mul_f32 v[60:61], v[60:61], v[194:195] op_sel_hi:[1,0]
	v_pk_mul_f32 v[50:51], v[50:51], v[194:195] op_sel_hi:[1,0]
	v_pk_mul_f32 v[48:49], v[48:49], v[194:195] op_sel_hi:[1,0]
	v_pk_mul_f32 v[34:35], v[34:35], v[194:195] op_sel_hi:[1,0]
	v_pk_mul_f32 v[32:33], v[32:33], v[194:195] op_sel_hi:[1,0]
	v_pk_mul_f32 v[194:195], v[194:195], v[196:197] op_sel_hi:[0,1]
	v_sub_f32_e32 v190, v190, v247
	v_sub_f32_e32 v189, v189, v247
	v_sub_f32_e32 v188, v188, v247
	v_sub_f32_e32 v187, v187, v247
	v_sub_f32_e32 v186, v186, v247
	v_sub_f32_e32 v185, v185, v247
	v_sub_f32_e32 v184, v184, v247
	v_sub_f32_e32 v183, v183, v247
	v_sub_f32_e32 v182, v182, v247
	v_sub_f32_e32 v181, v181, v247
	v_sub_f32_e32 v180, v180, v247
	v_sub_f32_e32 v175, v175, v247
	v_sub_f32_e32 v174, v174, v247
	v_sub_f32_e32 v173, v173, v247
	v_sub_f32_e32 v172, v172, v247
	v_cvt_pk_bf16_f32 v59, v194, v195
	v_sub_f32_e32 v43, v43, v247
	v_sub_f32_e32 v42, v42, v247
	v_sub_f32_e32 v41, v41, v247
	v_sub_f32_e32 v40, v40, v247

.LBB0_153:
	s_cmp_eq_u32 s100, 0
	s_cbranch_scc1 .Lfa1_nomid
	s_waitcnt lgkmcnt(0)
	s_barrier
.Lfa1_nomid:
	s_setprio 1
	v_add_f32_e32 v108, v108, v109
	v_add_f32_e32 v92, v92, v93
	s_waitcnt lgkmcnt(14)
	v_mfma_f32_16x16x32_bf16 v[120:123], v[156:159], v[72:75], v[120:123]
	v_exp_f32_e32 v188, v188
	v_exp_f32_e32 v189, v189
	v_mfma_f32_16x16x32_bf16 v[124:127], v[156:159], v[100:103], v[124:127]
	v_add_f32_e32 v109, v188, v189
	ds_read_b64_tr_b16 v[156:157], v246 offset:28672
	ds_read_b64_tr_b16 v[158:159], v246 offset:29696
	s_waitcnt lgkmcnt(14)
	v_mfma_f32_16x16x32_bf16 v[112:115], v[152:155], v[72:75], v[112:115]
	v_exp_f32_e32 v190, v190
	v_exp_f32_e32 v191, v191
	v_mfma_f32_16x16x32_bf16 v[116:119], v[152:155], v[100:103], v[116:119]
	v_add_f32_e32 v109, v109, v190
	v_add_f32_e32 v109, v109, v191
	ds_read_b64_tr_b16 v[152:153], v245 offset:28672
	ds_read_b64_tr_b16 v[154:155], v245 offset:29696
	s_waitcnt lgkmcnt(14)
	v_mfma_f32_16x16x32_bf16 v[96:99], v[148:151], v[72:75], v[96:99]
	v_exp_f32_e32 v184, v184
	v_exp_f32_e32 v185, v185
	v_mfma_f32_16x16x32_bf16 v[104:107], v[148:151], v[100:103], v[104:107]
	v_add_f32_e32 v109, v109, v184
	v_add_f32_e32 v109, v109, v185
	ds_read_b64_tr_b16 v[148:149], v244 offset:28672
	ds_read_b64_tr_b16 v[150:151], v244 offset:29696
	s_waitcnt lgkmcnt(14)
	v_mfma_f32_16x16x32_bf16 v[84:87], v[144:147], v[72:75], v[84:87]
	v_exp_f32_e32 v186, v186
	v_exp_f32_e32 v187, v187
	v_mfma_f32_16x16x32_bf16 v[88:91], v[144:147], v[100:103], v[88:91]
	v_add_f32_e32 v109, v109, v186
	v_add_f32_e32 v109, v109, v187
	ds_read_b64_tr_b16 v[144:145], v243 offset:28672
	ds_read_b64_tr_b16 v[146:147], v243 offset:29696
	s_waitcnt lgkmcnt(14)
	v_mfma_f32_16x16x32_bf16 v[68:71], v[140:143], v[72:75], v[68:71]
	v_exp_f32_e32 v194, v180
	v_exp_f32_e32 v195, v181
	v_mfma_f32_16x16x32_bf16 v[76:79], v[140:143], v[100:103], v[76:79]
	v_add_f32_e32 v109, v109, v194
	v_add_f32_e32 v109, v109, v195
	ds_read_b64_tr_b16 v[140:141], v242 offset:28672
	ds_read_b64_tr_b16 v[142:143], v242 offset:29696
	s_waitcnt lgkmcnt(14)
	v_mfma_f32_16x16x32_bf16 v[60:63], v[136:139], v[72:75], v[60:63]
	v_exp_f32_e32 v196, v182
	v_exp_f32_e32 v197, v183
	v_mfma_f32_16x16x32_bf16 v[64:67], v[136:139], v[100:103], v[64:67]
	v_add_f32_e32 v109, v109, v196
	v_add_f32_e32 v109, v109, v197
	ds_read_b64_tr_b16 v[136:137], v241 offset:28672
	ds_read_b64_tr_b16 v[138:139], v241 offset:29696
	s_waitcnt lgkmcnt(14)
	v_mfma_f32_16x16x32_bf16 v[48:51], v[132:135], v[72:75], v[48:51]
	v_exp_f32_e32 v172, v172
	v_exp_f32_e32 v173, v173
	v_mfma_f32_16x16x32_bf16 v[52:55], v[132:135], v[100:103], v[52:55]
	v_add_f32_e32 v109, v109, v172
	v_add_f32_e32 v109, v109, v173
	ds_read_b64_tr_b16 v[132:133], v240 offset:28672
	ds_read_b64_tr_b16 v[134:135], v240 offset:29696
	s_waitcnt lgkmcnt(14)
	v_mfma_f32_16x16x32_bf16 v[32:35], v[128:131], v[72:75], v[32:35]
	ds_read_b64_tr_b16 v[180:181], v239 offset:28672
	ds_read_b64_tr_b16 v[182:183], v239 offset:29696
	v_exp_f32_e32 v174, v174
	v_exp_f32_e32 v175, v175
	v_mfma_f32_16x16x32_bf16 v[36:39], v[128:131], v[100:103], v[36:39]
	v_add_f32_e32 v109, v109, v174
	v_add_f32_e32 v109, v109, v175
	s_waitcnt lgkmcnt(14)
	v_mfma_f32_16x16x32_bf16 v[120:123], v[156:159], v[56:59], v[120:123]
	v_exp_f32_e32 v100, v160
	v_exp_f32_e32 v101, v161
	v_cvt_pk_bf16_f32 v72, v188, v189
	v_mfma_f32_16x16x32_bf16 v[124:127], v[156:159], v[80:83], v[124:127]
	v_add_f32_e32 v93, v100, v101
	v_cvt_pk_bf16_f32 v73, v190, v191
	v_cvt_pk_bf16_f32 v74, v184, v185
	v_cvt_pk_bf16_f32 v75, v186, v187
	s_waitcnt lgkmcnt(12)
	v_mfma_f32_16x16x32_bf16 v[112:115], v[152:155], v[56:59], v[112:115]
	v_exp_f32_e32 v102, v162
	v_exp_f32_e32 v103, v163
	v_mfma_f32_16x16x32_bf16 v[116:119], v[152:155], v[80:83], v[116:119]
	v_add_f32_e32 v93, v93, v102
	v_add_f32_e32 v93, v93, v103
	s_waitcnt lgkmcnt(10)
	v_mfma_f32_16x16x32_bf16 v[96:99], v[148:151], v[56:59], v[96:99]
	v_exp_f32_e32 v152, v168
	v_exp_f32_e32 v153, v169
	v_mfma_f32_16x16x32_bf16 v[104:107], v[148:151], v[80:83], v[104:107]
	v_add_f32_e32 v93, v93, v152
	v_add_f32_e32 v93, v93, v153
	s_waitcnt lgkmcnt(8)
	v_mfma_f32_16x16x32_bf16 v[84:87], v[144:147], v[56:59], v[84:87]
	v_exp_f32_e32 v148, v170
	v_exp_f32_e32 v149, v171
	v_mfma_f32_16x16x32_bf16 v[88:91], v[144:147], v[80:83], v[88:91]
	v_add_f32_e32 v93, v93, v148
	v_add_f32_e32 v93, v93, v149
	s_waitcnt lgkmcnt(6)
	v_mfma_f32_16x16x32_bf16 v[68:71], v[140:143], v[56:59], v[68:71]
	v_cvt_pk_bf16_f32 v100, v100, v101
	v_cvt_pk_bf16_f32 v101, v102, v103
	v_cvt_pk_bf16_f32 v102, v152, v153
	v_mfma_f32_16x16x32_bf16 v[76:79], v[140:143], v[80:83], v[76:79]
	v_cvt_pk_bf16_f32 v103, v148, v149
	v_exp_f32_e32 v140, v164
	v_exp_f32_e32 v141, v165
	s_waitcnt lgkmcnt(4)
	v_mfma_f32_16x16x32_bf16 v[60:63], v[136:139], v[56:59], v[60:63]
	v_add_f32_e32 v93, v93, v140
	v_add_f32_e32 v93, v93, v141
	v_exp_f32_e32 v142, v166
	v_exp_f32_e32 v143, v167
	v_mfma_f32_16x16x32_bf16 v[64:67], v[136:139], v[80:83], v[64:67]
	v_add_f32_e32 v93, v93, v142
	v_add_f32_e32 v93, v93, v143
	s_waitcnt lgkmcnt(2)
	v_mfma_f32_16x16x32_bf16 v[48:51], v[132:135], v[56:59], v[48:51]
	v_exp_f32_e32 v136, v176
	v_exp_f32_e32 v137, v177
	v_mfma_f32_16x16x32_bf16 v[52:55], v[132:135], v[80:83], v[52:55]
	v_add_f32_e32 v93, v93, v136
	v_add_f32_e32 v93, v93, v137
	s_waitcnt lgkmcnt(0)
	v_mfma_f32_16x16x32_bf16 v[32:35], v[180:183], v[56:59], v[32:35]
	v_exp_f32_e32 v132, v178
	v_exp_f32_e32 v133, v179
	v_mfma_f32_16x16x32_bf16 v[36:39], v[180:183], v[80:83], v[36:39]
	v_add_f32_e32 v93, v93, v132
	v_add_f32_e32 v93, v93, v133
	s_setprio 0
	s_waitcnt lgkmcnt(0)
	s_cmp_lg_u32 s100, 0
	s_cbranch_scc1 .Lfa1_noend
	s_barrier
.Lfa1_noend:
	v_cvt_pk_bf16_f32 v56, v194, v195
	v_cvt_pk_bf16_f32 v57, v196, v197
	v_cvt_pk_bf16_f32 v58, v172, v173
	v_cvt_pk_bf16_f32 v59, v174, v175
	v_cvt_pk_bf16_f32 v80, v140, v141
	v_cvt_pk_bf16_f32 v81, v142, v143
	v_cvt_pk_bf16_f32 v82, v136, v137
	v_cvt_pk_bf16_f32 v83, v132, v133
	s_cmp_lg_u32 s82, s8
	s_cbranch_scc0 .LBB0_139
	s_mov_b32 s1, s8
	s_mov_b32 s98, s99
	s_add_i32 s99, s99, 0x9000
	s_cmp_eq_u32 s99, 0x1b000
	s_cselect_b32 s99, 0, s99
	s_branch .LBB0_147

	.amdhsa_kernel _Z14fwd_megakernel6Params
		.amdhsa_group_segment_fixed_size 0
		.amdhsa_private_segment_fixed_size 0
		.amdhsa_kernarg_size 488
		.amdhsa_user_sgpr_count 2
		.amdhsa_user_sgpr_dispatch_ptr 0
		.amdhsa_user_sgpr_queue_ptr 0
		.amdhsa_user_sgpr_kernarg_segment_ptr 1
		.amdhsa_user_sgpr_dispatch_id 0
		.amdhsa_user_sgpr_kernarg_preload_length 0
		.amdhsa_user_sgpr_kernarg_preload_offset 0
		.amdhsa_user_sgpr_private_segment_size 0
		.amdhsa_uses_dynamic_stack 0
		.amdhsa_enable_private_segment 0
		.amdhsa_system_sgpr_workgroup_id_x 1
		.amdhsa_system_sgpr_workgroup_id_y 0
		.amdhsa_system_sgpr_workgroup_id_z 0
		.amdhsa_system_sgpr_workgroup_info 0
		.amdhsa_system_vgpr_workitem_id 2
		.amdhsa_next_free_vgpr 256
		.amdhsa_next_free_sgpr 102
		.amdhsa_accum_offset 256
		.amdhsa_reserve_vcc 1
		.amdhsa_float_round_mode_32 0
		.amdhsa_float_round_mode_16_64 0
		.amdhsa_float_denorm_mode_32 3
		.amdhsa_float_denorm_mode_16_64 3
		.amdhsa_dx10_clamp 1
		.amdhsa_ieee_mode 1
		.amdhsa_fp16_overflow 0
		.amdhsa_tg_split 0
		.amdhsa_exception_fp_ieee_invalid_op 0
		.amdhsa_exception_fp_denorm_src 0
		.amdhsa_exception_fp_ieee_div_zero 0
		.amdhsa_exception_fp_ieee_overflow 0
		.amdhsa_exception_fp_ieee_underflow 0
		.amdhsa_exception_fp_ieee_inexact 0
		.amdhsa_exception_int_div_zero 0
	.end_amdhsa_kernel

amdhsa.kernels:
  - .agpr_count:     0
    .args:
      - .offset:         0
        .size:           232
        .value_kind:     by_value
      - .offset:         232
        .size:           4
        .value_kind:     hidden_block_count_x
      - .offset:         236
        .size:           4
        .value_kind:     hidden_block_count_y
      - .offset:         240
        .size:           4
        .value_kind:     hidden_block_count_z
      - .offset:         244
        .size:           2
        .value_kind:     hidden_group_size_x
      - .offset:         246
        .size:           2
        .value_kind:     hidden_group_size_y
      - .offset:         248
        .size:           2
        .value_kind:     hidden_group_size_z
      - .offset:         250
        .size:           2
        .value_kind:     hidden_remainder_x
      - .offset:         252
        .size:           2
        .value_kind:     hidden_remainder_y
      - .offset:         254
        .size:           2
        .value_kind:     hidden_remainder_z
      - .offset:         272
        .size:           8
        .value_kind:     hidden_global_offset_x
      - .offset:         280
        .size:           8
        .value_kind:     hidden_global_offset_y
      - .offset:         288
        .size:           8
        .value_kind:     hidden_global_offset_z
      - .offset:         296
        .size:           2
        .value_kind:     hidden_grid_dims
      - .offset:         320
        .size:           8
        .value_kind:     hidden_multigrid_sync_arg
      - .offset:         352
        .size:           4
        .value_kind:     hidden_dynamic_lds_size
    .group_segment_fixed_size: 0
    .kernarg_segment_align: 8
    .kernarg_segment_size: 488
    .language:       OpenCL C
    .language_version:
      - 2
      - 0
    .max_flat_workgroup_size: 512
    .name:           _Z14fwd_megakernel6Params
    .private_segment_fixed_size: 0
    .sgpr_count:     108
    .sgpr_spill_count: 18
    .symbol:         _Z14fwd_megakernel6Params.kd
    .uniform_work_group_size: 1
    .uses_dynamic_stack: false
    .vgpr_count:     256
    .vgpr_spill_count: 0
    .wavefront_size: 64
